# adds retention chunk-state stores transposed through LDS (full 256-B rows, dwordx4) instead of 8-byte scattered stores
# speedup vs baseline: 1.0078x; 1.0013x over previous
; #define LAS __attribute__((address_space(3)))
; DI int fresh_tid() { int t = threadIdx.x; asm volatile("" : "+v"(t)); return t; }
; DI void kv_chunk(CP p, int b, int n, LAS unsigned char* lds) {
;     const int tid = fresh_tid(), lane = tid & 63, wave = __builtin_amdgcn_readfirstlane(tid >> 6), g = lane >> 4, lr = lane & 15;
;     const bf16* proj = (const bf16*)(p->ws + WS_PROJ);
;     const int tok0 = b * SEQ + n * 64;
;     const bf16* rowb = proj + (size_t)tok0 * NPROJ;
;     constexpr int VT = 0, KT = 18432;
;     const int ve0 = tid >> 3, vp = tid & 7;
;     const int kj = tid & 63, kpt = tid >> 6;
;     {
;         u32x4 rv0, rv1, rk0, rk1;
;     ...
;         KVR_LOAD(0);
; DI void phase_prep(CP p, int l, LAS unsigned char* lds) {
;     ...
;         asm volatile("s_waitcnt vmcnt(0)" ::: "memory");
;         __syncthreads();
;         __builtin_amdgcn_fence(__ATOMIC_ACQUIRE, "agent");
.LBB0_296:
	v_mov_b32_e32 v33, v199
	s_waitcnt vmcnt(0)
	s_barrier
	s_waitcnt vmcnt(0)
	buffer_inv sc1
	s_add_u32 s52, s50, 0x2000
	v_ashrrev_i32_e32 v38, 6, v33
	v_ashrrev_i32_e32 v22, 4, v33
	v_and_b32_e32 v32, 63, v33
	v_add_u32_e32 v18, 32, v22
	v_lshlrev_b32_e32 v16, 3, v38
	v_ashrrev_i32_e32 v23, 31, v22
	v_ashrrev_i32_e32 v19, 31, v18
	v_lshlrev_b32_e32 v24, 14, v32
	v_mov_b32_e32 v25, v197
	v_ashrrev_i32_e32 v17, 31, v16
	s_addc_u32 s53, s51, 0
	v_lshlrev_b64 v[26:27], 14, v[22:23]
	v_lshlrev_b64 v[2:3], 14, v[18:19]
	v_lshl_add_u64 v[8:9], s[50:51], 0, v[24:25]
	v_lshlrev_b64 v[36:37], 1, v[16:17]
	v_and_b32_e32 v44, 15, v33
	v_lshl_add_u64 v[0:1], s[52:53], 0, v[26:27]
	v_lshl_add_u64 v[2:3], s[52:53], 0, v[2:3]
	v_lshl_add_u64 v[8:9], v[8:9], 0, v[36:37]
	s_mov_b64 s[52:53], 0x1c00
	s_movk_i32 s22, 0x1000
	v_lshlrev_b32_e32 v196, 4, v44
	v_lshl_add_u64 v[12:13], v[8:9], 0, s[52:53]
	v_add_co_u32_e32 v8, vcc, s22, v8
	v_lshl_add_u64 v[0:1], v[0:1], 0, v[196:197]
	v_lshl_add_u64 v[4:5], v[2:3], 0, v[196:197]
	v_addc_co_u32_e32 v9, vcc, 0, v9, vcc
	global_load_dwordx4 v[0:3], v[0:1], off
	s_nop 0
	global_load_dwordx4 v[4:7], v[4:5], off
	s_nop 0
	global_load_dwordx4 v[8:11], v[8:9], off offset:3072
	s_nop 0
	global_load_dwordx4 v[12:15], v[12:13], off offset:128
	v_readfirstlane_b32 s22, v38
	s_movk_i32 s52, 0x110
	s_lshl_b32 s60, s22, 4
	v_lshlrev_b64 v[28:29], 13, v[22:23]
	v_mul_lo_u32 v21, v22, s52
	v_or_b32_e32 v22, s60, v44
	s_movk_i32 s52, 0x90
	v_bfe_u32 v34, v33, 4, 2
	v_mul_lo_u32 v22, v22, s52
	v_add_u32_e32 v41, 0, v22
	v_lshlrev_b32_e32 v22, 3, v34
	v_bfe_u32 v23, v33, 2, 2
	s_ashr_i32 s61, s60, 31
	s_lshl_b32 s56, s56, 7
	v_or_b32_e32 v39, v22, v23
	v_lshlrev_b32_e32 v23, 3, v33
	s_lshl_b64 s[52:53], s[60:61], 1
	v_readlane_b32 s61, v254, 61
	v_and_b32_e32 v23, 24, v23
	s_add_u32 s52, s61, s52
	v_readlane_b32 s61, v254, 62
	v_add_u32_e32 v35, 0, v23
	s_addc_u32 s53, s61, s53
	v_mov_b32_e32 v23, v197
	v_lshl_add_u64 v[22:23], s[52:53], 0, v[22:23]
	s_movk_i32 s52, 0x480
	v_lshlrev_b64 v[30:31], 13, v[18:19]
	v_bitop3_b32 v19, v33, 63, v33 bitop3:0xc
	v_and_b32_e32 v47, 48, v33
	v_mul_lo_u32 v33, v38, s52
	s_lshl_b64 s[52:53], s[64:65], 14
	v_lshl_add_u64 v[24:25], s[52:53], 0, v[24:25]
	v_lshl_add_u64 v[26:27], v[26:27], 0, s[52:53]
	s_or_b32 s64, s56, s84
	v_readlane_b32 s84, v253, 47
	v_add_u32_e32 v40, 0, v21
	v_lshl_add_u32 v21, v32, 1, 0
	v_add_u32_e32 v42, 0x2400, v33
	v_mul_u32_u24_e32 v50, 0x110, v39
	v_lshlrev_b32_e32 v38, 8, v44
	v_mov_b32_e32 v39, v197
	v_lshl_add_u64 v[24:25], v[24:25], 0, v[36:37]
	v_or_b32_e32 v26, v26, v196
	v_readlane_b32 s85, v253, 48
	v_lshlrev_b32_e32 v20, 3, v44
	v_lshlrev_b32_e32 v18, 13, v32
	s_mov_b32 s57, 0
	v_cvt_f32_ubyte0_e32 v19, v19
	v_lshlrev_b32_e32 v34, 2, v34
	v_lshl_add_u64 v[22:23], v[22:23], 0, v[38:39]
	v_lshl_add_u64 v[24:25], s[12:13], 0, v[24:25]
	v_lshl_add_u64 v[26:27], s[12:13], 0, v[26:27]
	s_mov_b64 s[72:73], 0
	v_add_u32_e32 v36, v21, v42
	v_add_u32_e32 v37, v41, v47
	v_add_u32_e32 v48, v40, v196
	v_readlane_b32 s85, v253, 54
	v_and_b32_e32 v67, 15, v199
	v_mul_u32_u24_e32 v64, 0x110, v67
	v_bfe_u32 v67, v199, 4, 2
	v_lshl_add_u32 v64, v67, 3, v64
	v_lshrrev_b32_e32 v67, 6, v199
	v_lshl_add_u32 v64, v67, 5, v64
	v_add_u32_e32 v64, 0xa000, v64
	v_lshrrev_b32_e32 v67, 4, v199
	v_mul_u32_u24_e32 v65, 0x110, v67
	v_and_b32_e32 v67, 15, v199
	v_lshl_add_u32 v65, v67, 4, v65
	v_add_u32_e32 v65, 0xa000, v65
	v_lshlrev_b32_e32 v66, 4, v199
	v_mov_b32_e32 v67, 0
	v_readlane_b32 s100, v254, 61
	v_readlane_b32 s101, v254, 62
	s_nop 1
	v_lshl_add_u64 v[68:69], s[100:101], 0, v[66:67]
	s_branch .LBB0_298
; #define LAS __attribute__((address_space(3)))
; DI unsigned pk2(float lo, float hi) { f32x2_t v = {lo, hi}; bf16x2_t b = __builtin_convertvector(v, bf16x2_t); return __builtin_bit_cast(unsigned, b); }
; #define MFMA16(a, b, c) __builtin_amdgcn_mfma_f32_16x16x32_bf16((a), (b), (c), 0, 0, 0)
; DI void kv_chunk(CP p, int b, int n, LAS unsigned char* lds) {
;     ...
;             bf16x8 a[2];
; #pragma unroll
;             for (int ks = 0; ks < 2; ++ks) a[ks] = *(const LAS bf16x8*)(lds + KT + (16 * wave + lr) * 144 + ks * 64 + g * 16);
;             bf16* st = (bf16*)(p->ws + WS_RST) + (size_t)((((b * 4 + h) << 5) + n)) * 128 * 128;
;             bf16x8 bb[8][2];
; #pragma unroll
;             for (int et = 0; et < 8; ++et)
; #pragma unroll
;                 for (int ks = 0; ks < 2; ++ks) {
;                     const LAS unsigned char* vp_ = lds + VT + (32 * ks + 8 * g + (lr >> 2)) * 272 + et * 32 + 8 * (lr & 3);
;                     const v4i16_t lo = __builtin_amdgcn_ds_read_tr16_b64_v4i16((LAS v4i16_t*)vp_), hi = __builtin_amdgcn_ds_read_tr16_b64_v4i16((LAS v4i16_t*)(vp_ + 4 * 272));
;                     bb[et][ks] = (bf16x8){lo[0], lo[1], lo[2], lo[3], hi[0], hi[1], hi[2], hi[3]}; }
; #pragma unroll
;             for (int et = 0; et < 8; ++et) { f32x4 acc = {0.f, 0.f, 0.f, 0.f};
; #pragma unroll
;                 for (int ks = 0; ks < 2; ++ks) acc = MFMA16(a[ks], bb[et][ks], acc);
;                 u32x2 wv; wv.x = pk2(acc[0], acc[1]); wv.y = pk2(acc[2], acc[3]);
;                 *(u32x2*)(st + (size_t)(16 * et + lr) * 128 + 16 * wave + 4 * g) = wv; }
;             __syncthreads();
.LBB0_297:
	s_waitcnt lgkmcnt(0)
	s_barrier
	ds_read_b128 v[38:41], v37 offset:18432
	ds_read_b128 v[52:55], v37 offset:18496
	v_add_u32_e32 v42, v35, v50
	ds_read_b64_tr_b16 v[58:59], v42 offset:9792
	ds_read_b64_tr_b16 v[60:61], v42
	ds_read_b64_tr_b16 v[162:163], v42 offset:32
	ds_read_b64_tr_b16 v[166:167], v42 offset:64
	ds_read_b64_tr_b16 v[216:217], v42 offset:96
	ds_read_b64_tr_b16 v[62:63], v42 offset:1088
	ds_read_b64_tr_b16 v[164:165], v42 offset:1120
	ds_read_b64_tr_b16 v[168:169], v42 offset:1152
	ds_read_b64_tr_b16 v[218:219], v42 offset:1184
	ds_read_b64_tr_b16 v[56:57], v42 offset:8704
	ds_read_b64_tr_b16 v[220:221], v42 offset:8736
	ds_read_b64_tr_b16 v[232:233], v42 offset:8768
	ds_read_b64_tr_b16 v[236:237], v42 offset:8800
	s_waitcnt lgkmcnt(7)
	v_mfma_f32_16x16x32_bf16 v[60:63], v[38:41], v[60:63], 0
	ds_read_b64_tr_b16 v[222:223], v42 offset:9824
	ds_read_b64_tr_b16 v[234:235], v42 offset:9856
	ds_read_b64_tr_b16 v[238:239], v42 offset:9888
	s_ashr_i32 s65, s64, 31
	s_lshl_b64 s[52:53], s[64:65], 15
	s_waitcnt lgkmcnt(6)
	v_mfma_f32_16x16x32_bf16 v[56:59], v[52:55], v[56:59], v[60:63]
	s_nop 2
	ds_read_b64_tr_b16 v[60:61], v42 offset:128
	ds_read_b64_tr_b16 v[240:241], v42 offset:160
	ds_read_b64_tr_b16 v[244:245], v42 offset:192
	ds_read_b64_tr_b16 v[200:201], v42 offset:224
	ds_read_b64_tr_b16 v[62:63], v42 offset:1216
	ds_read_b64_tr_b16 v[242:243], v42 offset:1248
	ds_read_b64_tr_b16 v[246:247], v42 offset:1280
	ds_read_b64_tr_b16 v[202:203], v42 offset:1312
	s_add_i32 s57, s57, 1
	v_mfma_f32_16x16x32_bf16 v[162:165], v[38:41], v[162:165], 0
	v_cvt_pk_bf16_f32 v43, v58, v59
	s_add_u32 s72, s72, 0x100
	s_addc_u32 s73, s73, 0
	v_mfma_f32_16x16x32_bf16 v[166:169], v[38:41], v[166:169], 0
	s_add_i32 s64, s64, 32
	s_cmpk_eq_i32 s72, 0x400
	s_waitcnt lgkmcnt(10)
	v_mfma_f32_16x16x32_bf16 v[162:165], v[52:55], v[220:223], v[162:165]
	ds_read_b64_tr_b16 v[220:221], v42 offset:8832
	ds_read_b64_tr_b16 v[208:209], v42 offset:8864
	ds_read_b64_tr_b16 v[204:205], v42 offset:8896
	ds_read_b64_tr_b16 v[180:181], v42 offset:8928
	ds_read_b64_tr_b16 v[222:223], v42 offset:9920
	ds_read_b64_tr_b16 v[210:211], v42 offset:9952
	ds_read_b64_tr_b16 v[206:207], v42 offset:9984
	ds_read_b64_tr_b16 v[182:183], v42 offset:10016
	v_cvt_pk_bf16_f32 v42, v56, v57
	v_mfma_f32_16x16x32_bf16 v[56:59], v[38:41], v[216:219], 0
	s_waitcnt lgkmcnt(14)
	v_mfma_f32_16x16x32_bf16 v[166:169], v[52:55], v[232:235], v[166:169]
	v_lshl_add_u64 v[232:233], v[22:23], 0, s[52:53]
	ds_write_b64 v64, v[42:43]
	v_cvt_pk_bf16_f32 v42, v162, v163
	s_waitcnt lgkmcnt(11)
	v_mfma_f32_16x16x32_bf16 v[60:63], v[38:41], v[60:63], 0
	v_add_co_u32_e32 v162, vcc, s33, v232
	v_cvt_pk_bf16_f32 v43, v164, v165
	v_mfma_f32_16x16x32_bf16 v[56:59], v[52:55], v[236:239], v[56:59]
	v_addc_co_u32_e32 v163, vcc, 0, v233, vcc
	ds_write_b64 v64, v[42:43] offset:4352
	v_cvt_pk_bf16_f32 v42, v166, v167
	v_cvt_pk_bf16_f32 v43, v168, v169
	s_waitcnt lgkmcnt(3)
	v_mfma_f32_16x16x32_bf16 v[60:63], v[52:55], v[220:223], v[60:63]
	ds_write_b64 v64, v[42:43] offset:8704
	s_nop 0
	v_cvt_pk_bf16_f32 v42, v56, v57
	v_cvt_pk_bf16_f32 v43, v58, v59
	v_mfma_f32_16x16x32_bf16 v[56:59], v[38:41], v[240:243], 0
	v_add_co_u32_e32 v162, vcc, s19, v232
	s_nop 1
	v_addc_co_u32_e32 v163, vcc, 0, v233, vcc
	ds_write_b64 v64, v[42:43] offset:13056
	v_cvt_pk_bf16_f32 v42, v60, v61
	v_cvt_pk_bf16_f32 v43, v62, v63
	v_mfma_f32_16x16x32_bf16 v[60:63], v[38:41], v[244:247], 0
	ds_write_b64 v64, v[42:43] offset:17408
	v_mfma_f32_16x16x32_bf16 v[38:41], v[38:41], v[200:203], 0
	s_waitcnt lgkmcnt(2)
	v_mfma_f32_16x16x32_bf16 v[56:59], v[52:55], v[208:211], v[56:59]
	s_waitcnt lgkmcnt(0)
	v_mfma_f32_16x16x32_bf16 v[38:41], v[52:55], v[180:183], v[38:41]
	s_nop 5
	v_cvt_pk_bf16_f32 v42, v56, v57
	v_cvt_pk_bf16_f32 v43, v58, v59
	v_mfma_f32_16x16x32_bf16 v[56:59], v[52:55], v[204:207], v[60:63]
	v_cvt_pk_bf16_f32 v38, v38, v39
	v_cvt_pk_bf16_f32 v39, v40, v41
	s_nop 0
	v_add_co_u32_e32 v60, vcc, s11, v232
	s_nop 1
	v_addc_co_u32_e32 v61, vcc, 0, v233, vcc
	v_add_co_u32_e32 v40, vcc, s80, v232
	ds_write_b64 v64, v[42:43] offset:21760
	v_cvt_pk_bf16_f32 v42, v56, v57
	v_cvt_pk_bf16_f32 v43, v58, v59
	v_addc_co_u32_e32 v41, vcc, 0, v233, vcc
	ds_write_b64 v64, v[42:43] offset:26112
	ds_write_b64 v64, v[38:39] offset:30464
	s_waitcnt lgkmcnt(0)
	s_barrier
	s_cbranch_scc1 .LBB0_305

; #define LAS __attribute__((address_space(3)))
; DI unsigned pk2(float lo, float hi) { f32x2_t v = {lo, hi}; bf16x2_t b = __builtin_convertvector(v, bf16x2_t); return __builtin_bit_cast(unsigned, b); }
; DI void unpack8(const u32x4 w, float (&f)[8]) { f[0] = bflo(w.x); f[1] = bfhi(w.x); f[2] = bflo(w.y); f[3] = bfhi(w.y); f[4] = bflo(w.z); f[5] = bfhi(w.z); f[6] = bflo(w.w); f[7] = bfhi(w.w); }
; DI float fexp2(float x) { return __builtin_amdgcn_exp2f(x); }
; DI void kv_chunk(CP p, int b, int n, LAS unsigned char* lds) {
;     ...
;             const float w = fexp2((float)(63 - kj) * log2gamma(h));
;             *(LAS u32x4*)(lds + VT + (tid >> 4) * 272 + (tid & 15) * 16) = rv0; *(LAS u32x4*)(lds + VT + (32 + (tid >> 4)) * 272 + (tid & 15) * 16) = rv1;
;             { float x[8]; unpack8(rk0, x);
; #pragma unroll
;               for (int e = 0; e < 8; ++e) *(LAS bf16*)(lds + KT + (kpt * 8 + e) * 144 + kj * 2) = (bf16)(pk2(x[e] * w, 0.f) & 0xffffu);
;               unpack8(rk1, x);
; #pragma unroll
;               for (int e = 0; e < 8; ++e) *(LAS bf16*)(lds + KT + ((kpt + 8) * 8 + e) * 144 + kj * 2) = (bf16)(pk2(x[e] * w, 0.f) & 0xffffu); }
;             if (h < 3) KVR_LOAD(h + 1);
;             __syncthreads();
.LBB0_303:
	v_mul_f32_e32 v38, v38, v19
	v_exp_f32_e32 v38, v38
	s_waitcnt vmcnt(1)
	v_lshlrev_b32_e32 v39, 16, v8
	v_and_b32_e32 v40, 0xffff0000, v8
	v_add_u32_e32 v49, v21, v33
	v_mul_f32_e32 v39, v38, v39
	v_cvt_pk_bf16_f32 v39, v39, s0
	ds_write_b128 v48, v[0:3]
	ds_write_b128 v48, v[4:7] offset:8704
	ds_write_b16 v49, v39 offset:18432
	v_mul_f32_e32 v39, v38, v40
	v_lshlrev_b32_e32 v41, 16, v9
	v_cvt_pk_bf16_f32 v39, v39, s0
	ds_write_b16 v49, v39 offset:18576
	v_mul_f32_e32 v39, v38, v41
	v_and_b32_e32 v42, 0xffff0000, v9
	v_cvt_pk_bf16_f32 v39, v39, s0
	ds_write_b16 v49, v39 offset:18720
	v_mul_f32_e32 v39, v38, v42
	v_lshlrev_b32_e32 v43, 16, v10
	v_cvt_pk_bf16_f32 v39, v39, s0
	ds_write_b16 v49, v39 offset:18864
	v_mul_f32_e32 v39, v38, v43
	v_and_b32_e32 v45, 0xffff0000, v10
	v_cvt_pk_bf16_f32 v39, v39, s0
	ds_write_b16 v49, v39 offset:19008
	v_mul_f32_e32 v39, v38, v45
	v_lshlrev_b32_e32 v46, 16, v11
	v_cvt_pk_bf16_f32 v39, v39, s0
	ds_write_b16 v49, v39 offset:19152
	v_mul_f32_e32 v39, v38, v46
	v_and_b32_e32 v51, 0xffff0000, v11
	v_cvt_pk_bf16_f32 v39, v39, s0
	ds_write_b16 v49, v39 offset:19296
	v_mul_f32_e32 v39, v38, v51
	v_cvt_pk_bf16_f32 v39, v39, s0
	ds_write_b16 v49, v39 offset:19440
	s_waitcnt vmcnt(0)
	s_cmp_lt_i32 s57, 1
	s_cbranch_scc1 .Lkvl_skip
	s_add_i32 s100, s64, -32
	s_mov_b32 s101, 0
	s_lshl_b64 s[100:101], s[100:101], 15
	v_lshl_add_u64 v[70:71], v[68:69], 0, s[100:101]
	s_mov_b64 s[100:101], 0x2000
	v_lshl_add_u64 v[88:89], v[70:71], 0, s[100:101]
	v_lshl_add_u64 v[90:91], v[88:89], 0, s[100:101]
	v_lshl_add_u64 v[92:93], v[90:91], 0, s[100:101]
	ds_read_b128 v[72:75], v65
	ds_read_b128 v[76:79], v65 offset:8704
	ds_read_b128 v[80:83], v65 offset:17408
	ds_read_b128 v[84:87], v65 offset:26112
	s_waitcnt lgkmcnt(3)
	global_store_dwordx4 v[70:71], v[72:75], off
	s_waitcnt lgkmcnt(2)
	global_store_dwordx4 v[88:89], v[76:79], off
	s_waitcnt lgkmcnt(1)
	global_store_dwordx4 v[90:91], v[80:83], off
	s_waitcnt lgkmcnt(0)
	global_store_dwordx4 v[92:93], v[84:87], off

; DI void kv_chunk(CP p, int b, int n, LAS unsigned char* lds) {
;     ...
;             __syncthreads();
;         }
;     ...
;     }
;     {
;         u32x4 gv0, gv1, gk; f32x4 c0, c1, e0, e1;
;         const float* bcb = (const float*)(p->ws + WS_BCUM) + (size_t)tok0 * 256;
;     ...
;         KVG_LOAD(0);
.LBB0_305:
	s_add_i32 s100, s64, -32
	s_mov_b32 s101, 0
	s_lshl_b64 s[100:101], s[100:101], 15
	v_lshl_add_u64 v[70:71], v[68:69], 0, s[100:101]
	s_mov_b64 s[100:101], 0x2000
	v_lshl_add_u64 v[88:89], v[70:71], 0, s[100:101]
	v_lshl_add_u64 v[90:91], v[88:89], 0, s[100:101]
	v_lshl_add_u64 v[92:93], v[90:91], 0, s[100:101]
	ds_read_b128 v[72:75], v65
	ds_read_b128 v[76:79], v65 offset:8704
	ds_read_b128 v[80:83], v65 offset:17408
	ds_read_b128 v[84:87], v65 offset:26112
	s_waitcnt lgkmcnt(3)
	global_store_dwordx4 v[70:71], v[72:75], off
	s_waitcnt lgkmcnt(2)
	global_store_dwordx4 v[88:89], v[76:79], off
	s_waitcnt lgkmcnt(1)
	global_store_dwordx4 v[90:91], v[80:83], off
	s_waitcnt lgkmcnt(0)
	global_store_dwordx4 v[92:93], v[84:87], off
	s_or_b32 s52, s56, s55
	s_lshl_b64 s[48:49], s[48:49], 10
	v_readlane_b32 s53, v254, 40
	s_add_u32 s56, s53, s48
	v_readlane_b32 s48, v254, 41
	s_waitcnt vmcnt(9)
	v_lshlrev_b32_e32 v8, 1, v18
	v_mov_b32_e32 v9, v197
	s_addc_u32 s57, s48, s49
	v_lshl_add_u64 v[8:9], s[50:51], 0, v[8:9]
	s_add_u32 s48, s50, 0x2c00
	v_lshl_add_u64 v[38:39], v[16:17], 1, v[8:9]
	s_addc_u32 s49, s51, 0
	v_lshl_add_u64 v[36:37], v[16:17], 2, s[56:57]
	v_add_co_u32_e32 v8, vcc, s33, v38
	s_mov_b64 s[50:51], 0xfc00
	s_nop 0
	v_addc_co_u32_e32 v9, vcc, 0, v39, vcc
	v_lshl_add_u64 v[24:25], v[36:37], 0, s[50:51]
	s_mov_b32 s50, 0xf000
	v_lshl_add_u64 v[0:1], v[28:29], 1, s[48:49]
	v_lshlrev_b32_e32 v196, 1, v20
	v_lshl_add_u64 v[2:3], v[30:31], 1, s[48:49]
	v_lshlrev_b32_e32 v10, 10, v32
	v_mov_b32_e32 v11, v197
	v_add_co_u32_e32 v16, vcc, s50, v36
	v_lshl_add_u64 v[0:1], v[0:1], 0, v[196:197]
	v_lshl_add_u64 v[4:5], v[2:3], 0, v[196:197]
	v_lshl_add_u64 v[20:21], v[36:37], 0, v[10:11]
	v_addc_co_u32_e32 v17, vcc, 0, v37, vcc
	global_load_dwordx4 v[0:3], v[0:1], off
	s_nop 0
	global_load_dwordx4 v[4:7], v[4:5], off
	s_nop 0
	global_load_dwordx4 v[8:11], v[8:9], off offset:2560
	s_nop 0
	global_load_dwordx4 v[12:15], v[20:21], off
	s_nop 0
	global_load_dwordx4 v[16:19], v[16:17], off offset:3072
	s_nop 0
	global_load_dwordx4 v[20:23], v[20:21], off offset:16
	s_nop 0
	global_load_dwordx4 v[24:27], v[24:25], off offset:16
	s_and_b32 s53, s60, 48
	s_mov_b64 s[50:51], 0x2a00
	v_lshlrev_b32_e32 v46, 8, v32
	v_or_b32_e32 v32, s53, v44
	s_movk_i32 s55, 0x90
	v_lshl_add_u64 v[38:39], v[38:39], 0, s[50:51]
	s_and_b32 s51, s22, -4
	v_mad_u32_u24 v51, v32, s55, 0
	s_lshl_b32 s53, s53, 1
	v_readlane_b32 s55, v254, 63
	s_add_u32 s56, s55, s53
	v_readlane_b32 s53, v255, 0
	s_addc_u32 s57, s53, 0
	s_or_b32 s53, s51, 1
	s_or_b32 s55, s51, 2
	s_or_b32 s22, s22, 3
	v_lshlrev_b32_e32 v32, 1, v34
	v_lshl_or_b32 v34, s51, 4, v44
	v_lshl_or_b32 v40, s53, 4, v44
	v_lshl_or_b32 v42, s55, 4, v44
	v_lshl_or_b32 v44, s22, 4, v44
	v_mov_b32_e32 v33, v197
	v_lshl_add_u32 v52, s51, 5, v35
	v_lshl_add_u32 v53, s53, 5, v35
	v_lshl_add_u32 v54, s55, 5, v35
	v_lshl_add_u32 v55, s22, 5, v35
	v_ashrrev_i32_e32 v35, 31, v34
	v_ashrrev_i32_e32 v41, 31, v40
	v_ashrrev_i32_e32 v43, 31, v42
	v_ashrrev_i32_e32 v45, 31, v44
	s_mov_b32 s50, 0
	v_lshl_add_u64 v[32:33], s[56:57], 0, v[32:33]
	v_lshlrev_b64 v[34:35], 7, v[34:35]
	v_lshlrev_b64 v[40:41], 7, v[40:41]
	v_lshlrev_b64 v[42:43], 7, v[42:43]
	v_lshlrev_b64 v[44:45], 7, v[44:45]
	v_lshlrev_b32_e32 v46, 2, v46
	v_add_u32_e32 v51, v51, v47
	v_add_u32_e32 v52, v52, v50
	v_add_u32_e32 v53, v53, v50
	v_add_u32_e32 v54, v54, v50
	v_add_u32_e32 v50, v55, v50
	v_readlane_b32 s65, v253, 53
	s_branch .LBB0_307

; __global__ void __launch_bounds__(512) fwd_megakernel(Params p_unused) {
;     extern __shared__ __attribute__((aligned(16))) unsigned char lds_raw[];
	.amdhsa_kernel _Z14fwd_megakernel6Params
		.amdhsa_group_segment_fixed_size 0
		.amdhsa_private_segment_fixed_size 0
		.amdhsa_kernarg_size 448
		.amdhsa_user_sgpr_count 2
		.amdhsa_user_sgpr_dispatch_ptr 0
		.amdhsa_user_sgpr_queue_ptr 0
		.amdhsa_user_sgpr_kernarg_segment_ptr 1
		.amdhsa_user_sgpr_dispatch_id 0
		.amdhsa_user_sgpr_kernarg_preload_length 0
		.amdhsa_user_sgpr_kernarg_preload_offset 0
		.amdhsa_user_sgpr_private_segment_size 0
		.amdhsa_uses_dynamic_stack 0
		.amdhsa_enable_private_segment 0
		.amdhsa_system_sgpr_workgroup_id_x 1
		.amdhsa_system_sgpr_workgroup_id_y 0
		.amdhsa_system_sgpr_workgroup_id_z 0
		.amdhsa_system_sgpr_workgroup_info 0
		.amdhsa_system_vgpr_workitem_id 2
		.amdhsa_next_free_vgpr 256
		.amdhsa_next_free_sgpr 102
		.amdhsa_accum_offset 256
		.amdhsa_reserve_vcc 1
		.amdhsa_float_round_mode_32 0
		.amdhsa_float_round_mode_16_64 0
		.amdhsa_float_denorm_mode_32 3
		.amdhsa_float_denorm_mode_16_64 3
		.amdhsa_dx10_clamp 1
		.amdhsa_ieee_mode 1
		.amdhsa_fp16_overflow 0
		.amdhsa_tg_split 0
		.amdhsa_exception_fp_ieee_invalid_op 0
		.amdhsa_exception_fp_denorm_src 0
		.amdhsa_exception_fp_ieee_div_zero 0
		.amdhsa_exception_fp_ieee_overflow 0
		.amdhsa_exception_fp_ieee_underflow 0
		.amdhsa_exception_fp_ieee_inexact 0
		.amdhsa_exception_int_div_zero 0
	.end_amdhsa_kernel

; #define LAS __attribute__((address_space(3)))
; __global__ void __launch_bounds__(512) fwd_megakernel(Params p_unused) {
;     extern __shared__ __attribute__((aligned(16))) unsigned char lds_raw[];
;     LAS unsigned char* lds = (LAS unsigned char*)lds_raw;
amdhsa.kernels:
  - .agpr_count:     0
    .args:
      - .offset:         0
        .size:           192
        .value_kind:     by_value
      - .offset:         192
        .size:           4
        .value_kind:     hidden_block_count_x
      - .offset:         196
        .size:           4
        .value_kind:     hidden_block_count_y
      - .offset:         200
        .size:           4
        .value_kind:     hidden_block_count_z
      - .offset:         204
        .size:           2
        .value_kind:     hidden_group_size_x
      - .offset:         206
        .size:           2
        .value_kind:     hidden_group_size_y
      - .offset:         208
        .size:           2
        .value_kind:     hidden_group_size_z
      - .offset:         210
        .size:           2
        .value_kind:     hidden_remainder_x
      - .offset:         212
        .size:           2
        .value_kind:     hidden_remainder_y
      - .offset:         214
        .size:           2
        .value_kind:     hidden_remainder_z
      - .offset:         232
        .size:           8
        .value_kind:     hidden_global_offset_x
      - .offset:         240
        .size:           8
        .value_kind:     hidden_global_offset_y
      - .offset:         248
        .size:           8
        .value_kind:     hidden_global_offset_z
      - .offset:         256
        .size:           2
        .value_kind:     hidden_grid_dims
      - .offset:         280
        .size:           8
        .value_kind:     hidden_multigrid_sync_arg
      - .offset:         312
        .size:           4
        .value_kind:     hidden_dynamic_lds_size
    .group_segment_fixed_size: 0
    .kernarg_segment_align: 8
    .kernarg_segment_size: 448
    .language:       OpenCL C
    .language_version:
      - 2
      - 0
    .max_flat_workgroup_size: 512
    .name:           _Z14fwd_megakernel6Params
    .private_segment_fixed_size: 0
    .sgpr_count:     108
    .sgpr_spill_count: 261
    .symbol:         _Z14fwd_megakernel6Params.kd
    .uniform_work_group_size: 1
    .uses_dynamic_stack: false
    .vgpr_count:     256
    .vgpr_spill_count: 0
    .wavefront_size: 64
